# C pair tile: log2e folded into Q prescale, QK accumulators land in v208-239, 16 v_mul + 8 v_pk_mul per tile removed
# baseline (speedup 1.0000x reference)
.LBB0_160:
	s_sub_i32 s3, s2, s13
	s_max_i32 s2, s3, 0xffffffe4
	s_add_i32 s6, s3, 31
	s_lshl_b32 s3, s3, 6
	s_addk_i32 s3, 0x780
	s_add_i32 s18, s12, s3
	v_mad_i64_i32 v[18:19], s[20:21], s18, v200, v[114:115]
	global_load_dwordx4 v[6:9], v[18:19], off
	global_load_dwordx4 v[10:13], v[18:19], off offset:32
	global_load_dwordx4 v[14:17], v[18:19], off offset:64
	global_load_dwordx4 v[2:5], v[18:19], off offset:96
	global_load_dwordx4 v[92:95], v[18:19], off offset:3072
	global_load_dwordx4 v[88:91], v[18:19], off offset:3104
	global_load_dwordx4 v[84:87], v[18:19], off offset:3136
	global_load_dwordx4 v[80:83], v[18:19], off offset:3168
	s_add_i32 s2, s2, 28
	s_cmp_le_i32 s6, s2
	s_waitcnt vmcnt(7)
	v_lshlrev_b32_e32 v0, 16, v6
	v_mul_f32_e32 v0, 0x3e38aa3b, v0
	v_and_b32_e32 v6, 0xffff0000, v6
	v_mul_f32_e32 v6, 0x3e38aa3b, v6
	v_cvt_pk_bf16_f32 v96, v0, v6
	v_lshlrev_b32_e32 v0, 16, v7
	v_mul_f32_e32 v0, 0x3e38aa3b, v0
	v_and_b32_e32 v6, 0xffff0000, v7
	v_mul_f32_e32 v6, 0x3e38aa3b, v6
	v_cvt_pk_bf16_f32 v97, v0, v6
	v_lshlrev_b32_e32 v0, 16, v8
	v_mul_f32_e32 v0, 0x3e38aa3b, v0
	v_and_b32_e32 v6, 0xffff0000, v8
	v_mul_f32_e32 v6, 0x3e38aa3b, v6
	v_cvt_pk_bf16_f32 v98, v0, v6
	v_lshlrev_b32_e32 v0, 16, v9
	v_mul_f32_e32 v0, 0x3e38aa3b, v0
	v_and_b32_e32 v6, 0xffff0000, v9
	v_mul_f32_e32 v6, 0x3e38aa3b, v6
	v_cvt_pk_bf16_f32 v99, v0, v6
	s_waitcnt vmcnt(6)
	v_lshlrev_b32_e32 v0, 16, v10
	v_mul_f32_e32 v0, 0x3e38aa3b, v0
	v_and_b32_e32 v6, 0xffff0000, v10
	v_mul_f32_e32 v6, 0x3e38aa3b, v6
	v_cvt_pk_bf16_f32 v100, v0, v6
	v_lshlrev_b32_e32 v0, 16, v11
	v_mul_f32_e32 v0, 0x3e38aa3b, v0
	v_and_b32_e32 v6, 0xffff0000, v11
	v_mul_f32_e32 v6, 0x3e38aa3b, v6
	v_cvt_pk_bf16_f32 v101, v0, v6
	v_lshlrev_b32_e32 v0, 16, v12
	v_mul_f32_e32 v0, 0x3e38aa3b, v0
	v_and_b32_e32 v6, 0xffff0000, v12
	v_mul_f32_e32 v6, 0x3e38aa3b, v6
	v_cvt_pk_bf16_f32 v102, v0, v6
	v_lshlrev_b32_e32 v0, 16, v13
	v_mul_f32_e32 v0, 0x3e38aa3b, v0
	v_and_b32_e32 v6, 0xffff0000, v13
	v_mul_f32_e32 v6, 0x3e38aa3b, v6
	v_cvt_pk_bf16_f32 v103, v0, v6
	s_waitcnt vmcnt(5)
	v_lshlrev_b32_e32 v0, 16, v14
	v_mul_f32_e32 v0, 0x3e38aa3b, v0
	v_and_b32_e32 v6, 0xffff0000, v14
	v_mul_f32_e32 v6, 0x3e38aa3b, v6
	v_cvt_pk_bf16_f32 v104, v0, v6
	v_lshlrev_b32_e32 v0, 16, v15
	v_mul_f32_e32 v0, 0x3e38aa3b, v0
	v_and_b32_e32 v6, 0xffff0000, v15
	v_mul_f32_e32 v6, 0x3e38aa3b, v6
	v_cvt_pk_bf16_f32 v105, v0, v6
	v_lshlrev_b32_e32 v0, 16, v16
	v_mul_f32_e32 v0, 0x3e38aa3b, v0
	v_and_b32_e32 v6, 0xffff0000, v16
	v_mul_f32_e32 v6, 0x3e38aa3b, v6
	v_cvt_pk_bf16_f32 v106, v0, v6
	v_lshlrev_b32_e32 v0, 16, v17
	v_mul_f32_e32 v0, 0x3e38aa3b, v0
	v_and_b32_e32 v6, 0xffff0000, v17
	v_mul_f32_e32 v6, 0x3e38aa3b, v6
	v_cvt_pk_bf16_f32 v107, v0, v6
	s_waitcnt vmcnt(4)
	v_lshlrev_b32_e32 v0, 16, v2
	v_and_b32_e32 v2, 0xffff0000, v2
	v_mul_f32_e32 v0, 0x3e38aa3b, v0
	v_mul_f32_e32 v2, 0x3e38aa3b, v2
	v_cvt_pk_bf16_f32 v108, v0, v2
	v_lshlrev_b32_e32 v0, 16, v3
	v_and_b32_e32 v2, 0xffff0000, v3
	v_mul_f32_e32 v0, 0x3e38aa3b, v0
	v_mul_f32_e32 v2, 0x3e38aa3b, v2
	v_cvt_pk_bf16_f32 v109, v0, v2
	v_lshlrev_b32_e32 v0, 16, v4
	v_and_b32_e32 v2, 0xffff0000, v4
	v_mul_f32_e32 v0, 0x3e38aa3b, v0
	v_mul_f32_e32 v2, 0x3e38aa3b, v2
	v_cvt_pk_bf16_f32 v110, v0, v2
	v_lshlrev_b32_e32 v0, 16, v5
	v_and_b32_e32 v2, 0xffff0000, v5
	v_mul_f32_e32 v0, 0x3e38aa3b, v0
	v_mul_f32_e32 v2, 0x3e38aa3b, v2
	v_cvt_pk_bf16_f32 v111, v0, v2
	s_cbranch_scc1 .LBB0_158
	v_mov_b32_e32 v14, v1
	v_mov_b32_e32 v15, v1
	s_ashr_i32 s3, s3, 6
	v_mov_b32_e32 v0, v1
	v_mov_b32_e32 v2, v1
	v_mov_b32_e32 v3, v1
	v_mov_b32_e32 v4, v1
	v_mov_b32_e32 v5, v1
	v_mov_b32_e32 v6, v1
	v_mov_b32_e32 v7, v1
	v_mov_b32_e32 v8, v1
	v_mov_b32_e32 v9, v1
	v_mov_b32_e32 v10, v1
	v_mov_b32_e32 v11, v1
	v_mov_b32_e32 v12, v1
	v_mov_b32_e32 v13, v1
	v_mov_b64_e32 v[30:31], v[14:15]
	v_mov_b64_e32 v[46:47], v[14:15]
	s_add_i32 s19, s3, -2
	v_mov_b32_e32 v118, v116
	v_mov_b64_e32 v[28:29], v[12:13]
	v_mov_b64_e32 v[26:27], v[10:11]
	v_mov_b64_e32 v[24:25], v[8:9]
	v_mov_b64_e32 v[22:23], v[6:7]
	v_mov_b64_e32 v[20:21], v[4:5]
	v_mov_b64_e32 v[18:19], v[2:3]
	v_mov_b64_e32 v[16:17], v[0:1]
	v_mov_b64_e32 v[44:45], v[12:13]
	v_mov_b64_e32 v[42:43], v[10:11]
	v_mov_b64_e32 v[40:41], v[8:9]
	v_mov_b64_e32 v[38:39], v[6:7]
	v_mov_b64_e32 v[36:37], v[4:5]
	v_mov_b64_e32 v[34:35], v[2:3]
	v_mov_b64_e32 v[32:33], v[0:1]
	v_mov_b32_e32 v117, v129
	s_branch .LBB0_164

.LBB0_164:
	s_add_i32 s20, s6, -1
	s_cmp_le_i32 s20, s3
	s_cselect_b64 s[22:23], -1, 0
	s_cmp_gt_i32 s6, s19
	s_cselect_b64 s[24:25], -1, 0
	s_and_b64 s[22:23], s[22:23], s[24:25]
	s_andn2_b64 vcc, exec, s[22:23]
	s_cbranch_vccnz .LBB0_162
	s_and_b32 s21, s20, 3
	s_mul_i32 s7, s21, 0x2400
	v_add_u32_e32 v0, s7, v139
	ds_read_b128 v[2:5], v0
	s_cmp_lt_i32 s6, 33
	s_cselect_b64 s[6:7], -1, 0
	s_and_b64 vcc, exec, s[6:7]
	s_waitcnt lgkmcnt(0)
	v_mfma_f32_32x32x16_bf16 v[208:223], v[2:5], v[96:99], 0
	ds_read_b128 v[2:5], v0 offset:4608
	s_waitcnt lgkmcnt(0)
	v_mfma_f32_32x32x16_bf16 v[224:239], v[2:5], v[96:99], 0
	ds_read_b128 v[2:5], v0 offset:32
	s_waitcnt lgkmcnt(0)
	v_mfma_f32_32x32x16_bf16 v[208:223], v[2:5], v[100:103], v[208:223]
	ds_read_b128 v[2:5], v0 offset:4640
	s_waitcnt lgkmcnt(0)
	v_mfma_f32_32x32x16_bf16 v[224:239], v[2:5], v[100:103], v[224:239]
	ds_read_b128 v[2:5], v0 offset:64
	s_waitcnt lgkmcnt(0)
	v_mfma_f32_32x32x16_bf16 v[208:223], v[2:5], v[104:107], v[208:223]
	ds_read_b128 v[2:5], v0 offset:4672
	s_waitcnt lgkmcnt(0)
	v_mfma_f32_32x32x16_bf16 v[224:239], v[2:5], v[104:107], v[224:239]
	ds_read_b128 v[2:5], v0 offset:96
	s_waitcnt lgkmcnt(0)
	v_mfma_f32_32x32x16_bf16 v[208:223], v[2:5], v[108:111], v[208:223]
	ds_read_b128 v[2:5], v0 offset:4704
	s_waitcnt lgkmcnt(0)
	v_mfma_f32_32x32x16_bf16 v[224:239], v[2:5], v[108:111], v[224:239]
	s_cbranch_vccnz .LBB0_167
	s_nop 10
	v_mov_b32_e32 v224, 0xff800000
	v_mov_b32_e32 v225, v224
	v_mov_b32_e32 v226, v224
	v_mov_b32_e32 v227, v224
	v_mov_b32_e32 v228, v224
	v_mov_b32_e32 v229, v224
	v_mov_b32_e32 v230, v224
	v_mov_b32_e32 v231, v224
	v_mov_b32_e32 v232, v224
	v_mov_b32_e32 v233, v224
	v_mov_b32_e32 v234, v224
	v_mov_b32_e32 v235, v224
	v_mov_b32_e32 v236, v224
	v_mov_b32_e32 v237, v224
	v_mov_b32_e32 v238, v224
	v_mov_b32_e32 v239, v224
	s_branch .LBB0_168

.LBB0_168:
	v_max3_f32 v0, v225, v209, v226
	v_max3_f32 v0, v0, v227, v208
	v_max3_f32 v0, v0, v224, v210
	v_max3_f32 v0, v0, v211, v228
	v_max3_f32 v0, v0, v229, v212
	v_max3_f32 v0, v0, v213, v230
	v_max3_f32 v0, v0, v231, v214
	v_max3_f32 v0, v0, v215, v232
	v_max3_f32 v0, v0, v233, v216
	v_max3_f32 v0, v0, v217, v234
	v_max3_f32 v0, v0, v235, v218
	v_max3_f32 v0, v0, v219, v236
	v_max3_f32 v0, v0, v237, v220
	v_max3_f32 v0, v0, v221, v238
	v_max3_f32 v0, v0, v239, v222
	v_max3_f32 v0, v0, v223, v223
	v_and_b32_e32 v53, 64, v199
	v_xor_b32_e32 v52, 32, v199
	v_add_u32_e32 v53, 64, v53
	v_cmp_lt_i32_e32 vcc, v52, v53
	s_nop 1
	v_cndmask_b32_e32 v52, v199, v52, vcc
	v_lshlrev_b32_e32 v52, 2, v52
	ds_bpermute_b32 v52, v52, v0
	s_waitcnt lgkmcnt(0)
	v_max3_f32 v52, v118, v0, v52
	v_sub_f32_e32 v0, v118, v52
	v_exp_f32_e32 v0, v0
	s_nop 0
	v_cmp_eq_f32_e32 vcc, 1.0, v0
	s_cmp_eq_u64 vcc, exec
	s_cbranch_scc1 .LBB0_170
	v_pk_mul_f32 v[46:47], v[46:47], v[0:1] op_sel_hi:[1,0]
	v_pk_mul_f32 v[44:45], v[44:45], v[0:1] op_sel_hi:[1,0]
	v_pk_mul_f32 v[42:43], v[42:43], v[0:1] op_sel_hi:[1,0]
	v_pk_mul_f32 v[40:41], v[40:41], v[0:1] op_sel_hi:[1,0]
	v_pk_mul_f32 v[38:39], v[38:39], v[0:1] op_sel_hi:[1,0]
	v_pk_mul_f32 v[36:37], v[36:37], v[0:1] op_sel_hi:[1,0]
	v_pk_mul_f32 v[34:35], v[34:35], v[0:1] op_sel_hi:[1,0]
	v_pk_mul_f32 v[32:33], v[32:33], v[0:1] op_sel_hi:[1,0]
	v_pk_mul_f32 v[30:31], v[30:31], v[0:1] op_sel_hi:[1,0]
	v_pk_mul_f32 v[28:29], v[28:29], v[0:1] op_sel_hi:[1,0]
	v_pk_mul_f32 v[26:27], v[26:27], v[0:1] op_sel_hi:[1,0]
	v_pk_mul_f32 v[24:25], v[24:25], v[0:1] op_sel_hi:[1,0]
	v_pk_mul_f32 v[22:23], v[22:23], v[0:1] op_sel_hi:[1,0]
	v_pk_mul_f32 v[20:21], v[20:21], v[0:1] op_sel_hi:[1,0]
	v_pk_mul_f32 v[18:19], v[18:19], v[0:1] op_sel_hi:[1,0]
	v_pk_mul_f32 v[16:17], v[16:17], v[0:1] op_sel_hi:[1,0]
.LBB0_170:
	v_sub_f32_e32 v12, v228, v52
	v_exp_f32_e32 v61, v12
	v_sub_f32_e32 v12, v213, v52
	v_sub_f32_e32 v15, v227, v52
	v_exp_f32_e32 v60, v12
	v_sub_f32_e32 v12, v229, v52
	v_sub_f32_e32 v10, v230, v52
	v_sub_f32_e32 v8, v232, v52
	v_sub_f32_e32 v6, v234, v52
	v_sub_f32_e32 v4, v236, v52
	v_sub_f32_e32 v53, v208, v52
	v_sub_f32_e32 v54, v224, v52
	v_sub_f32_e32 v56, v225, v52
	v_exp_f32_e32 v59, v15
	v_sub_f32_e32 v15, v212, v52
	v_exp_f32_e32 v63, v12
	v_sub_f32_e32 v12, v214, v52
	v_exp_f32_e32 v65, v10
	v_sub_f32_e32 v10, v215, v52
	v_exp_f32_e32 v69, v8
	v_sub_f32_e32 v8, v217, v52
	v_exp_f32_e32 v73, v6
	v_sub_f32_e32 v6, v219, v52
	v_exp_f32_e32 v77, v4
	v_sub_f32_e32 v4, v221, v52
	v_sub_f32_e32 v2, v238, v52
	v_exp_f32_e32 v55, v54
	v_sub_f32_e32 v54, v209, v52
	v_sub_f32_e32 v14, v226, v52
	v_exp_f32_e32 v64, v10
	v_sub_f32_e32 v10, v231, v52
	v_exp_f32_e32 v68, v8
	v_sub_f32_e32 v8, v233, v52
	v_exp_f32_e32 v72, v6
	v_sub_f32_e32 v6, v235, v52
	v_exp_f32_e32 v76, v4
	v_sub_f32_e32 v4, v237, v52
	v_exp_f32_e32 v119, v2
	v_sub_f32_e32 v2, v223, v52
	v_exp_f32_e32 v57, v56
	v_sub_f32_e32 v56, v210, v52
	v_exp_f32_e32 v58, v14
	v_sub_f32_e32 v14, v211, v52
	v_exp_f32_e32 v67, v10
	v_sub_f32_e32 v10, v216, v52
	v_exp_f32_e32 v71, v8
	v_sub_f32_e32 v8, v218, v52
	v_exp_f32_e32 v75, v6
	v_sub_f32_e32 v6, v220, v52
	v_exp_f32_e32 v79, v4
	v_sub_f32_e32 v4, v222, v52
	v_exp_f32_e32 v118, v2
	v_sub_f32_e32 v2, v239, v52
	s_mulk_i32 s21, 0x3000
	v_exp_f32_e32 v53, v53
	v_exp_f32_e32 v54, v54
	v_exp_f32_e32 v56, v56
	v_exp_f32_e32 v14, v14
	v_exp_f32_e32 v15, v15
	v_exp_f32_e32 v62, v12
	v_exp_f32_e32 v66, v10
	v_exp_f32_e32 v70, v8
	v_exp_f32_e32 v74, v6
	v_exp_f32_e32 v78, v4
	v_exp_f32_e32 v120, v2
	v_add_u32_e32 v121, s21, v135
	ds_read_b64_tr_b16 v[172:173], v121 offset:0
	ds_read_b64_tr_b16 v[174:175], v121 offset:1536
	ds_read_b64_tr_b16 v[168:169], v121 offset:64
	ds_read_b64_tr_b16 v[170:171], v121 offset:1600
	ds_read_b64_tr_b16 v[164:165], v121 offset:3072
	ds_read_b64_tr_b16 v[166:167], v121 offset:4608
	ds_read_b64_tr_b16 v[122:123], v121 offset:3136
	ds_read_b64_tr_b16 v[124:125], v121 offset:4672
	ds_read_b64_tr_b16 v[48:49], v121 offset:6144
	ds_read_b64_tr_b16 v[50:51], v121 offset:7680
	ds_read_b64_tr_b16 v[10:11], v121 offset:6208
	ds_read_b64_tr_b16 v[12:13], v121 offset:7744
	ds_read_b64_tr_b16 v[6:7], v121 offset:9216
	ds_read_b64_tr_b16 v[8:9], v121 offset:10752
	ds_read_b64_tr_b16 v[2:3], v121 offset:9280
	ds_read_b64_tr_b16 v[4:5], v121 offset:10816
	s_waitcnt lgkmcnt(0)
	v_cvt_pk_bf16_f32 v176, v53, v54
	v_cvt_pk_bf16_f32 v177, v56, v14
	v_cvt_pk_bf16_f32 v178, v15, v60
	v_cvt_pk_bf16_f32 v179, v62, v64
	s_andn2_b64 vcc, exec, s[6:7]
	v_mfma_f32_32x32x16_bf16 v[32:47], v[172:175], v[176:179], v[32:47]
	v_mfma_f32_32x32x16_bf16 v[16:31], v[168:171], v[176:179], v[16:31]
	v_cvt_pk_bf16_f32 v168, v66, v68
	v_cvt_pk_bf16_f32 v169, v70, v72
	v_cvt_pk_bf16_f32 v170, v74, v76
	v_cvt_pk_bf16_f32 v171, v78, v118
	s_nop 0
	v_mfma_f32_32x32x16_bf16 v[32:47], v[164:167], v[168:171], v[32:47]
	v_mfma_f32_32x32x16_bf16 v[16:31], v[122:125], v[168:171], v[16:31]
	s_cbranch_vccnz .LBB0_172
	v_cvt_pk_bf16_f32 v122, v55, v57
	v_cvt_pk_bf16_f32 v123, v58, v59
	v_cvt_pk_bf16_f32 v124, v61, v63
	v_cvt_pk_bf16_f32 v125, v65, v67
	s_nop 0
	v_mfma_f32_32x32x16_bf16 v[32:47], v[48:51], v[122:125], v[32:47]
	v_mfma_f32_32x32x16_bf16 v[16:31], v[10:13], v[122:125], v[16:31]
	v_cvt_pk_bf16_f32 v10, v69, v71
	v_cvt_pk_bf16_f32 v11, v73, v75
	v_cvt_pk_bf16_f32 v12, v77, v79
	v_cvt_pk_bf16_f32 v13, v119, v120
	s_nop 0
	v_mfma_f32_32x32x16_bf16 v[32:47], v[6:9], v[10:13], v[32:47]
	v_mfma_f32_32x32x16_bf16 v[16:31], v[2:5], v[10:13], v[16:31]
